# GEMM unit boundary: halves stay one barrier apart across units (no alignment barrier before a non-final epilogue, no re-stagger after)
# baseline (speedup 1.0000x reference)
.Lk_done:
	s_add_u32 s52, s0, 0x80
	s_addc_u32 s53, s1, 0
	v_lshl_add_u64 v[144:145], s[52:53], 0, v[136:137]
	s_add_i32 m0, s9, 0xc000
	global_load_lds_dwordx4 v[144:145], off
	v_lshl_add_u64 v[144:145], s[52:53], 0, v[138:139]
	s_add_i32 m0, s9, 0xe000
	s_nop 0
	global_load_lds_dwordx4 v[144:145], off
	v_readlane_b32 s42, v233, 50
	v_readlane_b32 s43, v233, 51
	s_and_b64 s[42:43], s[42:43], s[40:41]
	s_and_b64 vcc, exec, s[42:43]
	s_cbranch_vccz .LBB0_336
	s_barrier

.LBB0_394:
	s_nop 0
	v_pk_mul_f32 v[6:7], v[6:7], v[14:15]
	v_pk_mul_f32 v[4:5], v[4:5], v[12:13]
	v_pk_mul_f32 v[10:11], v[2:3], v[10:11]
	v_pk_mul_f32 v[2:3], v[0:1], v[8:9]
	v_lshl_add_u64 v[16:17], s[48:49], 0, v[32:33]
	v_cvt_pk_bf16_f32 v0, v4, v5
	v_cvt_pk_bf16_f32 v1, v6, v7
	v_cvt_pk_bf16_f32 v2, v2, v3
	v_cvt_pk_bf16_f32 v3, v10, v11
	global_store_dwordx4 v[16:17], v[0:3], off
	s_and_b64 vcc, exec, s[40:41]
	s_mov_b64 s[40:41], -1
	s_cbranch_vccnz .LBB0_325
.LBB0_395:
	s_branch .LBB0_324
.LBB0_397:
	v_readlane_b32 s86, v233, 26
	v_readlane_b32 s68, v233, 29
	v_readlane_b32 s64, v233, 31
	v_readlane_b32 s87, v233, 27
	v_readlane_b32 s98, v233, 28
	v_readlane_b32 s69, v233, 30
	v_readlane_b32 s65, v233, 32
	v_readlane_b32 s99, v233, 33
	v_readlane_b32 s70, v233, 34
	s_mov_b64 s[78:79], s[56:57]
	s_mov_b32 s76, s58
	s_cbranch_execz .LBB0_307
	s_branch .LBB0_511
